# P0 queue: ticket prefetched one item ahead, LDS broadcast via ds ops (no per-item vmcnt drain)
# baseline (speedup 1.0000x reference)
; DEV void phase0(const Params& p) {
;     ...
;   while (true) {
;     __syncthreads();
;     if (tidx == 0) *slot = first ? (int)blockIdx.x : (int)(gridDim.x + atomicAdd(ctr, 1u));
;     first = false;
;     __syncthreads();
;     const int it = __builtin_amdgcn_readfirstlane(*slot);
;     if (it >= total) break;
.LBB0_2113:
	s_andn2_b64 vcc, exec, s[0:1]
	s_mov_b64 s[6:7], 0
	s_cbranch_vccnz .LBB0_2114
	s_waitcnt vmcnt(0)
	s_getpc_b64 s[98:99]

; DEV void phase0(const Params& p) {
;     ...
;     __syncthreads();
;     if (tidx == 0) *slot = first ? (int)blockIdx.x : (int)(gridDim.x + atomicAdd(ctr, 1u));
;     first = false;
;     __syncthreads();
;     const int it = __builtin_amdgcn_readfirstlane(*slot);
;     if (it >= total) break;
.LBB0_2114:
	s_waitcnt lgkmcnt(0)
	s_barrier
	s_and_saveexec_b64 s[0:1], s[34:35]
	s_cbranch_execz .LBB0_2120
	s_xor_b64 s[6:7], s[6:7], -1
	s_andn2_b64 vcc, exec, s[6:7]
	v_mov_b32_e32 v0, s70
	s_cbranch_vccnz .Lp0q_first
	s_load_dword s7, s[84:85], 0x0
	s_waitcnt vmcnt(8)
	v_readfirstlane_b32 s6, v250
	s_waitcnt lgkmcnt(0)
	s_add_i32 s7, s7, s6
	v_mov_b32_e32 v0, s7
.Lp0q_first:
	v_mov_b32_e32 v2, 0x20800
	v_mov_b32_e32 v251, 1
	ds_write_b32 v2, v0
	global_atomic_add v250, v177, v251, s[36:37] sc0
	s_waitcnt lgkmcnt(0)
.LBB0_2120:
	s_or_b64 exec, exec, s[0:1]
	v_mov_b32_e32 v0, 0x20800
	s_waitcnt lgkmcnt(0)
	s_barrier
	ds_read_b32 v0, v0
	s_mov_b64 s[0:1], -1
	s_waitcnt lgkmcnt(0)
	v_readfirstlane_b32 s66, v0
	s_cmpk_gt_i32 s66, 0x90f
	s_cbranch_scc1 .LBB0_2113
	s_cmpk_gt_i32 s66, 0x7f
	s_cbranch_scc0 .LBB0_2146
	s_cmpk_gt_u32 s66, 0x8f
	s_cbranch_scc0 .LBB0_2144
	s_add_i32 s14, s66, 0xffffff70
	s_lshr_b32 s7, s14, 3
	s_cmpk_gt_u32 s14, 0x57f
	s_cbranch_scc0 .LBB0_2129
	s_cmpk_gt_u32 s14, 0x67f
	s_cbranch_scc0 .LBB0_2130
	s_cmpk_gt_u32 s14, 0x6ff
	s_cbranch_scc0 .LBB0_2131
	s_cmpk_gt_u32 s14, 0x77f
	s_cbranch_scc0 .LBB0_2132
	s_lshl_b32 s12, s7, 7
	s_cmpk_gt_u32 s14, 0x7ff
	s_cbranch_scc0 .LBB0_2133
	s_add_i32 s92, s12, 0xffff8000
	s_lshl_b64 s[0:1], s[92:93], 12
	v_readlane_b32 s8, v253, 6
	s_add_u32 s0, s8, s0
	v_readlane_b32 s8, v253, 7
	s_addc_u32 s1, s8, s1
	s_mov_b64 s[8:9], s[58:59]
	s_cbranch_execz .LBB0_2134
	s_branch .LBB0_2135
